# P9 row-norm exchange: partial sums read with device-scope loads instead of a full cache invalidate by every wave; init-flag acquire invalidate dropped (barrier words are only touched by atomics and de
# speedup vs baseline: 1.0334x; 1.0178x over previous
; #define LAS __attribute__((address_space(3)))
; __device__ __forceinline__ unsigned xb_add(unsigned* p, unsigned v) { return __hip_atomic_fetch_add(p, v, __ATOMIC_RELAXED, __HIP_MEMORY_SCOPE_AGENT); }
; __device__ __forceinline__ unsigned xb_xcc_id() { return (unsigned)__builtin_amdgcn_s_getreg((3 << 11) | 20) & 0xFu; }
; __device__ __forceinline__ XcdBarrier xcd_barrier_post(unsigned* bar, volatile LAS unsigned* st) {
;     XcdBarrier b; b.bar = bar; b.x = xb_xcc_id(); b.st = st;
;     if (threadIdx.x == 0) (void)xb_add(&bar[XB_XCNT(b.x)], 1u);
;     return b;
; __global__ void __launch_bounds__(512, 2) fwd_megakernel(Params p) {
;     ...
;         } else if (threadIdx.x == 0) {
;             unsigned sp = 0; while (__hip_atomic_load(flag, __ATOMIC_RELAXED, __HIP_MEMORY_SCOPE_AGENT) != MAGIC) { __builtin_amdgcn_s_sleep(1); if (++sp > (1u << 22)) break; }
;             __builtin_amdgcn_fence(__ATOMIC_ACQUIRE, "agent");
;         }
;         __syncthreads();
;     }
;     const XcdBarrier xb = xcd_barrier_post(barw, bst);
.Linit_acq:
.Linit_post:
	v_readlane_b32 s2, v255, 1
	s_nop 3
	s_lshl_b32 s2, s2, 8
	v_mov_b32_e32 v0, s2
	v_mov_b32_e32 v1, 1
	global_atomic_add v0, v1, s[96:97] offset:1024

;     __device__ __forceinline__ void operator()(f32x4 (&acc)[2][2][4][2], const Unit& u, int wr, int wc, int fr, int fq) const {
;     ...
;         unsigned* pc = cnt + 64 * u.pm;
;         if ((threadIdx.x & 63) == 0) __hip_atomic_fetch_add(pc, 1u, __ATOMIC_RELAXED, __HIP_MEMORY_SCOPE_AGENT);
;         { unsigned sp = 0; while ((unsigned)__builtin_amdgcn_readfirstlane(__hip_atomic_load(pc, __ATOMIC_RELAXED, __HIP_MEMORY_SCOPE_AGENT)) < 32u) { __builtin_amdgcn_s_sleep(2); if (++sp > (1u << 20)) break; } }
;         __builtin_amdgcn_fence(__ATOMIC_ACQUIRE, "agent");
;         f32x4 gv[2][2];
; #pragma unroll
;         for (int bj = 0; bj < 2; ++bj) { gv[bj][0] = *(const f32x4*)(gf + col0 + bj * HALF); gv[bj][1] = *(const f32x4*)(gf + col0 + bj * HALF + 4); }
;         f32x4 ptv[2][4];
; #pragma unroll
;         for (int ai = 0; ai < 2; ++ai)
; #pragma unroll
;             for (int m = 0; m < 4; ++m) ptv[ai][m] = *(const f32x4*)(ss + (size_t)(row0 + ai * HALF + m * 16) * 16 + fq * 4);
; #pragma unroll
;         for (int ai = 0; ai < 2; ++ai)
; #pragma unroll
;             for (int m = 0; m < 4; ++m) {
;                 const int row = row0 + ai * HALF + m * 16; const size_t off = (size_t)row * DM + col0;
;                 const f32x4 pt = ptv[ai][m];
;                 float s = (pt[0] + pt[1]) + (pt[2] + pt[3]); s += __shfl_xor(s, 16); s += __shfl_xor(s, 32);
;                 const float r = 1.0f / sqrtf(s * (1.0f / 1024.0f) + 1e-6f);
; #pragma unroll
;                 for (int bj = 0; bj < 2; ++bj) { *(f32x4*)(out + off + bj * HALF) = acc[ai][bj][m][0] * r * gv[bj][0]; *(f32x4*)(out + off + bj * HALF + 4) = acc[ai][bj][m][1] * r * gv[bj][1]; }
.LBB0_1468:
	s_waitcnt lgkmcnt(0)
	v_lshl_add_u64 v[2:3], v[152:153], 0, v[200:201]
	v_lshl_add_u64 v[6:7], v[152:153], 0, v[202:203]
	global_load_dwordx4 v[2:5], v[2:3], off sc1
	v_lshlrev_b64 v[190:191], 2, v[190:191]
	global_load_dwordx4 v[6:9], v[6:7], off sc1
	v_lshl_add_u64 v[10:11], v[152:153], 0, v[204:205]
	v_lshl_add_u64 v[204:205], v[152:153], 0, v[0:1]
	v_lshl_add_u64 v[12:13], v[152:153], 0, v[206:207]
	v_lshl_add_u64 v[14:15], v[152:153], 0, v[208:209]
	v_lshl_add_u64 v[18:19], v[152:153], 0, v[32:33]
	v_lshl_add_u64 v[20:21], s[68:69], 0, v[190:191]
	global_load_dwordx4 v[200:203], v[10:11], off sc1
	global_load_dwordx4 v[32:35], v[12:13], off sc1
	global_load_dwordx4 v[28:31], v[14:15], off sc1
	global_load_dwordx4 v[24:27], v[18:19], off sc1
	v_lshl_add_u64 v[16:17], v[152:153], 0, v[16:17]
	v_lshlrev_b64 v[176:177], 12, v[176:177]
	v_lshl_add_u64 v[176:177], s[70:71], 0, v[176:177]
	v_lshl_add_u64 v[176:177], v[176:177], 0, v[190:191]
	s_waitcnt vmcnt(5)
	v_mov_b32_e32 v0, v3
	v_mov_b32_e32 v1, v4
	v_mov_b32_e32 v3, v5
	s_waitcnt vmcnt(4)
	v_mov_b32_e32 v4, v7
	v_mov_b32_e32 v5, v8
	v_mov_b32_e32 v7, v9
	v_pk_add_f32 v[0:1], v[0:1], v[2:3]
	v_pk_add_f32 v[2:3], v[4:5], v[6:7]
	v_add_f32_e32 v18, v0, v1
	v_add_f32_e32 v19, v2, v3
	global_load_dwordx4 v[8:11], v[20:21], off offset:16
	global_load_dwordx4 v[12:15], v[20:21], off
	global_load_dwordx4 v[0:3], v[20:21], off offset:528
	global_load_dwordx4 v[4:7], v[20:21], off offset:512
	ds_bpermute_b32 v22, v219, v18
	ds_bpermute_b32 v23, v219, v19
	s_waitcnt lgkmcnt(1)
	v_add_f32_e32 v206, v18, v22
	s_waitcnt lgkmcnt(0)
	v_add_f32_e32 v207, v19, v23
	ds_bpermute_b32 v208, v220, v206
	ds_bpermute_b32 v209, v220, v207
	global_load_dwordx4 v[20:23], v[16:17], off sc1
	s_nop 0
	global_load_dwordx4 v[16:19], v[204:205], off sc1
	s_waitcnt lgkmcnt(1)
	v_add_f32_e32 v204, v206, v208
	s_waitcnt lgkmcnt(0)
	v_add_f32_e32 v205, v207, v209
	v_fmamk_f32 v204, v204, 0x3a800000, v217
	v_fmamk_f32 v205, v205, 0x3a800000, v217
	v_mul_f32_e32 v206, 0x4f800000, v204
	v_cmp_gt_f32_e32 vcc, s43, v204
	v_mul_f32_e32 v207, 0x4f800000, v205
	v_cmp_gt_f32_e64 s[6:7], s43, v205
	v_cndmask_b32_e32 v204, v204, v206, vcc
	v_sqrt_f32_e32 v206, v204
	v_cndmask_b32_e64 v205, v205, v207, s[6:7]
	v_sqrt_f32_e32 v207, v205
	v_add_u32_e32 v208, -1, v206
	v_fma_f32 v223, -v208, v206, v204
	v_add_u32_e32 v221, -1, v207
	v_add_u32_e32 v209, 1, v206
	v_fma_f32 v225, -v221, v207, v205
	v_cmp_ge_f32_e64 s[10:11], 0, v223
	v_add_u32_e32 v222, 1, v207
	v_fma_f32 v224, -v209, v206, v204
	v_cndmask_b32_e64 v206, v206, v208, s[10:11]
	v_cmp_ge_f32_e64 s[10:11], 0, v225
	v_fma_f32 v226, -v222, v207, v205
	s_nop 0
	v_cndmask_b32_e64 v207, v207, v221, s[10:11]
	v_cmp_lt_f32_e64 s[10:11], 0, v224
	s_nop 1
	v_cndmask_b32_e64 v206, v206, v209, s[10:11]
	v_cmp_lt_f32_e64 s[10:11], 0, v226
	v_mul_f32_e32 v208, 0x37800000, v206
	v_cndmask_b32_e32 v206, v206, v208, vcc
	v_cndmask_b32_e64 v207, v207, v222, s[10:11]
	v_mul_f32_e32 v209, 0x37800000, v207
	v_cmp_class_f32_e32 vcc, v204, v218
	v_cndmask_b32_e64 v207, v207, v209, s[6:7]
	s_nop 0
	v_cndmask_b32_e32 v204, v206, v204, vcc
	v_cmp_class_f32_e32 vcc, v205, v218
	s_nop 1
	v_cndmask_b32_e32 v221, v207, v205, vcc
	v_div_scale_f32 v205, s[6:7], v204, v204, 1.0
	v_rcp_f32_e32 v208, v205
	v_div_scale_f32 v207, s[6:7], v221, v221, 1.0
	v_rcp_f32_e32 v209, v207
	v_fma_f32 v223, -v205, v208, 1.0
	v_div_scale_f32 v206, vcc, 1.0, v204, 1.0
	v_fmac_f32_e32 v208, v223, v208
	v_mul_f32_e32 v223, v206, v208
	v_fma_f32 v224, -v207, v209, 1.0
	v_fma_f32 v225, -v205, v223, v206
	v_div_scale_f32 v222, s[6:7], 1.0, v221, 1.0
	v_fmac_f32_e32 v209, v224, v209
	v_fmac_f32_e32 v223, v225, v208
	v_mul_f32_e32 v224, v222, v209
	v_fma_f32 v205, -v205, v223, v206
	v_fma_f32 v226, -v207, v224, v222
	v_div_fmas_f32 v205, v205, v208, v223
	v_fmac_f32_e32 v224, v226, v209
	v_div_fixup_f32 v204, v205, v204, 1.0
	v_fma_f32 v206, -v207, v224, v222
	s_mov_b64 vcc, s[6:7]
	v_pk_mul_f32 v[124:125], v[124:125], v[204:205] op_sel_hi:[1,0]
	v_pk_mul_f32 v[126:127], v[126:127], v[204:205] op_sel_hi:[1,0]
	v_pk_mul_f32 v[120:121], v[120:121], v[204:205] op_sel_hi:[1,0]
	v_div_fmas_f32 v224, v206, v209, v224
	v_pk_mul_f32 v[122:123], v[122:123], v[204:205] op_sel_hi:[1,0]
	v_pk_mul_f32 v[206:207], v[116:117], v[204:205] op_sel_hi:[1,0]
	v_pk_mul_f32 v[208:209], v[118:119], v[204:205] op_sel_hi:[1,0]
	v_pk_mul_f32 v[222:223], v[112:113], v[204:205] op_sel_hi:[1,0]
	v_pk_mul_f32 v[204:205], v[114:115], v[204:205] op_sel_hi:[1,0]
	s_waitcnt vmcnt(4)
	v_pk_mul_f32 v[114:115], v[14:15], v[126:127]
	v_pk_mul_f32 v[112:113], v[12:13], v[124:125]
	v_pk_mul_f32 v[116:117], v[8:9], v[120:121]
	v_div_fixup_f32 v224, v224, v221, 1.0
	v_pk_mul_f32 v[118:119], v[10:11], v[122:123]
	s_waitcnt vmcnt(2)
	v_pk_mul_f32 v[122:123], v[6:7], v[208:209]
	v_pk_mul_f32 v[120:121], v[4:5], v[206:207]
	v_pk_mul_f32 v[126:127], v[2:3], v[204:205]
	v_pk_mul_f32 v[124:125], v[0:1], v[222:223]
	global_store_dwordx4 v[176:177], v[112:115], off
	global_store_dwordx4 v[176:177], v[116:119], off offset:16
	global_store_dwordx4 v[176:177], v[120:123], off offset:512
	global_store_dwordx4 v[176:177], v[124:127], off offset:528
	v_lshlrev_b64 v[116:117], 12, v[174:175]
	v_pk_mul_f32 v[112:113], v[188:189], v[224:225] op_sel_hi:[1,0]
	v_pk_mul_f32 v[114:115], v[184:185], v[224:225] op_sel_hi:[1,0]
	v_lshl_add_u64 v[116:117], s[70:71], 0, v[116:117]
	v_pk_mul_f32 v[114:115], v[14:15], v[114:115]
	v_pk_mul_f32 v[112:113], v[12:13], v[112:113]
	v_lshl_add_u64 v[116:117], v[116:117], 0, v[190:191]
	global_store_dwordx4 v[116:117], v[112:115], off
	v_pk_mul_f32 v[106:107], v[106:107], v[224:225] op_sel_hi:[1,0]
	s_nop 0
	v_mov_b32_e32 v114, v201
	v_mov_b32_e32 v115, v202
	v_mov_b32_e32 v201, v203
	v_pk_add_f32 v[114:115], v[114:115], v[200:201]
	v_pk_mul_f32 v[112:113], v[186:187], v[224:225] op_sel_hi:[1,0]
	v_add_f32_e32 v118, v114, v115
	ds_bpermute_b32 v119, v219, v118
	v_pk_mul_f32 v[114:115], v[10:11], v[106:107]
	v_pk_mul_f32 v[112:113], v[8:9], v[112:113]
	global_store_dwordx4 v[116:117], v[112:115], off offset:16
	v_pk_mul_f32 v[106:107], v[150:151], v[224:225] op_sel_hi:[1,0]
	s_waitcnt lgkmcnt(0)
;     __device__ __forceinline__ void operator()(f32x4 (&acc)[2][2][4][2], const Unit& u, int wr, int wc, int fr, int fq) const {
;     ...
; #pragma unroll
;         for (int ai = 0; ai < 2; ++ai)
; #pragma unroll
;             for (int m = 0; m < 4; ++m) {
;                 const int row = row0 + ai * HALF + m * 16; const size_t off = (size_t)row * DM + col0;
;                 const f32x4 pt = ptv[ai][m];
;                 float s = (pt[0] + pt[1]) + (pt[2] + pt[3]); s += __shfl_xor(s, 16); s += __shfl_xor(s, 32);
;                 const float r = 1.0f / sqrtf(s * (1.0f / 1024.0f) + 1e-6f);
; #pragma unroll
;                 for (int bj = 0; bj < 2; ++bj) { *(f32x4*)(out + off + bj * HALF) = acc[ai][bj][m][0] * r * gv[bj][0]; *(f32x4*)(out + off + bj * HALF + 4) = acc[ai][bj][m][1] * r * gv[bj][1]; }
	v_add_f32_e32 v118, v118, v119
	ds_bpermute_b32 v119, v220, v118
	v_pk_mul_f32 v[112:113], v[146:147], v[224:225] op_sel_hi:[1,0]
	s_nop 0
	v_pk_mul_f32 v[114:115], v[6:7], v[112:113]
	v_pk_mul_f32 v[112:113], v[4:5], v[106:107]
	s_waitcnt lgkmcnt(0)
	v_add_f32_e32 v106, v118, v119
	v_fmamk_f32 v106, v106, 0x3a800000, v217
	v_mul_f32_e32 v107, 0x4f800000, v106
	v_cmp_gt_f32_e32 vcc, s43, v106
	global_store_dwordx4 v[116:117], v[112:115], off offset:512
	s_nop 0
	v_cndmask_b32_e32 v118, v106, v107, vcc
	v_sqrt_f32_e32 v119, v118
	v_pk_mul_f32 v[106:107], v[148:149], v[224:225] op_sel_hi:[1,0]
	v_pk_mul_f32 v[112:113], v[144:145], v[224:225] op_sel_hi:[1,0]
	v_add_u32_e32 v114, -1, v119
	v_fma_f32 v115, -v114, v119, v118
	v_cmp_ge_f32_e64 s[6:7], 0, v115
	v_add_u32_e32 v115, 1, v119
	s_nop 0
	v_cndmask_b32_e64 v114, v119, v114, s[6:7]
	v_fma_f32 v119, -v115, v119, v118
	v_cmp_lt_f32_e64 s[6:7], 0, v119
	s_nop 1
	v_cndmask_b32_e64 v114, v114, v115, s[6:7]
	v_mul_f32_e32 v115, 0x37800000, v114
	v_cndmask_b32_e32 v114, v114, v115, vcc
	v_cmp_class_f32_e32 vcc, v118, v218
	s_nop 1
	v_cndmask_b32_e32 v118, v114, v118, vcc
	v_div_scale_f32 v119, s[6:7], v118, v118, 1.0
	v_rcp_f32_e32 v120, v119
	v_pk_mul_f32 v[114:115], v[2:3], v[112:113]
	v_pk_mul_f32 v[112:113], v[0:1], v[106:107]
	global_store_dwordx4 v[116:117], v[112:115], off offset:528
	v_fma_f32 v106, -v119, v120, 1.0
	v_fmac_f32_e32 v120, v106, v120
	v_div_scale_f32 v106, vcc, 1.0, v118, 1.0
	v_mul_f32_e32 v107, v106, v120
	v_fma_f32 v112, -v119, v107, v106
	v_fmac_f32_e32 v107, v112, v120
	v_fma_f32 v106, -v119, v107, v106
	v_div_fmas_f32 v106, v106, v120, v107
	v_div_fixup_f32 v106, v106, v118, 1.0
	v_lshlrev_b64 v[116:117], 12, v[172:173]
	v_pk_mul_f32 v[112:113], v[182:183], v[106:107] op_sel_hi:[1,0]
	v_pk_mul_f32 v[114:115], v[178:179], v[106:107] op_sel_hi:[1,0]
	v_lshl_add_u64 v[116:117], s[70:71], 0, v[116:117]
	v_pk_mul_f32 v[114:115], v[14:15], v[114:115]
	v_pk_mul_f32 v[112:113], v[12:13], v[112:113]
	v_lshl_add_u64 v[116:117], v[116:117], 0, v[190:191]
	global_store_dwordx4 v[116:117], v[112:115], off
	s_nop 1
	v_mov_b32_e32 v114, v33
	v_mov_b32_e32 v115, v34
	v_mov_b32_e32 v33, v35
	v_pk_add_f32 v[32:33], v[114:115], v[32:33]
	v_pk_mul_f32 v[112:113], v[180:181], v[106:107] op_sel_hi:[1,0]
	v_add_f32_e32 v107, v32, v33
	ds_bpermute_b32 v114, v219, v107
	v_pk_mul_f32 v[32:33], v[96:97], v[106:107] op_sel_hi:[1,0]
	s_waitcnt lgkmcnt(0)
	v_add_f32_e32 v96, v107, v114
	ds_bpermute_b32 v97, v220, v96
	v_pk_mul_f32 v[34:35], v[10:11], v[32:33]
	v_pk_mul_f32 v[32:33], v[8:9], v[112:113]
	global_store_dwordx4 v[116:117], v[32:35], off offset:16
	s_waitcnt lgkmcnt(0)
	v_add_f32_e32 v96, v96, v97
	v_fmamk_f32 v96, v96, 0x3a800000, v217
	v_mul_f32_e32 v97, 0x4f800000, v96
	v_cmp_gt_f32_e32 vcc, s43, v96
	v_pk_mul_f32 v[32:33], v[140:141], v[106:107] op_sel_hi:[1,0]
	v_pk_mul_f32 v[34:35], v[136:137], v[106:107] op_sel_hi:[1,0]
	v_cndmask_b32_e32 v96, v96, v97, vcc
	v_sqrt_f32_e32 v97, v96
	v_pk_mul_f32 v[34:35], v[6:7], v[34:35]
	v_pk_mul_f32 v[32:33], v[4:5], v[32:33]
	global_store_dwordx4 v[116:117], v[32:35], off offset:512
	s_nop 1
	v_pk_mul_f32 v[32:33], v[138:139], v[106:107] op_sel_hi:[1,0]
	v_pk_mul_f32 v[34:35], v[108:109], v[106:107] op_sel_hi:[1,0]
	v_add_u32_e32 v106, -1, v97
	v_fma_f32 v107, -v106, v97, v96
	v_cmp_ge_f32_e64 s[6:7], 0, v107
	v_add_u32_e32 v107, 1, v97
	v_pk_mul_f32 v[34:35], v[2:3], v[34:35]
	v_cndmask_b32_e64 v106, v97, v106, s[6:7]
	v_fma_f32 v97, -v107, v97, v96
	v_cmp_lt_f32_e64 s[6:7], 0, v97
	v_pk_mul_f32 v[32:33], v[0:1], v[32:33]
	global_store_dwordx4 v[116:117], v[32:35], off offset:528
	v_cndmask_b32_e64 v97, v106, v107, s[6:7]
	v_mul_f32_e32 v106, 0x37800000, v97
	v_cndmask_b32_e32 v97, v97, v106, vcc
	v_cmp_class_f32_e32 vcc, v96, v218
	s_nop 1
	v_cndmask_b32_e32 v96, v97, v96, vcc
	v_div_scale_f32 v97, s[6:7], v96, v96, 1.0
	v_rcp_f32_e32 v106, v97
	s_nop 0
	v_fma_f32 v32, -v97, v106, 1.0
	v_fmac_f32_e32 v106, v32, v106
	v_div_scale_f32 v32, vcc, 1.0, v96, 1.0
	v_mul_f32_e32 v33, v32, v106
	v_fma_f32 v34, -v97, v33, v32
	v_fmac_f32_e32 v33, v34, v106
	v_fma_f32 v32, -v97, v33, v32
	v_div_fmas_f32 v32, v32, v106, v33
	v_div_fixup_f32 v96, v32, v96, 1.0
	v_lshlrev_b64 v[106:107], 12, v[162:163]
	v_pk_mul_f32 v[32:33], v[142:143], v[96:97] op_sel_hi:[1,0]
	v_pk_mul_f32 v[34:35], v[132:133], v[96:97] op_sel_hi:[1,0]
	v_lshl_add_u64 v[106:107], s[70:71], 0, v[106:107]
	v_pk_mul_f32 v[34:35], v[14:15], v[34:35]
	v_pk_mul_f32 v[32:33], v[12:13], v[32:33]
	v_lshl_add_u64 v[106:107], v[106:107], 0, v[190:191]
	global_store_dwordx4 v[106:107], v[32:35], off
	s_nop 1
	v_mov_b32_e32 v34, v29
	v_mov_b32_e32 v35, v30
	v_mov_b32_e32 v29, v31
	v_pk_add_f32 v[28:29], v[34:35], v[28:29]
	v_pk_mul_f32 v[32:33], v[134:135], v[96:97] op_sel_hi:[1,0]
	v_add_f32_e32 v34, v28, v29
	ds_bpermute_b32 v35, v219, v34
	v_pk_mul_f32 v[28:29], v[94:95], v[96:97] op_sel_hi:[1,0]
	s_nop 0
	v_pk_mul_f32 v[30:31], v[10:11], v[28:29]
	v_pk_mul_f32 v[28:29], v[8:9], v[32:33]
	s_waitcnt lgkmcnt(0)
	v_add_f32_e32 v32, v34, v35
	ds_bpermute_b32 v33, v220, v32
	global_store_dwordx4 v[106:107], v[28:31], off offset:16
	s_waitcnt lgkmcnt(0)
;     __device__ __forceinline__ void operator()(f32x4 (&acc)[2][2][4][2], const Unit& u, int wr, int wc, int fr, int fq) const {
;     ...
; #pragma unroll
;         for (int ai = 0; ai < 2; ++ai)
; #pragma unroll
;             for (int m = 0; m < 4; ++m) {
;                 const int row = row0 + ai * HALF + m * 16; const size_t off = (size_t)row * DM + col0;
;                 const f32x4 pt = ptv[ai][m];
;                 float s = (pt[0] + pt[1]) + (pt[2] + pt[3]); s += __shfl_xor(s, 16); s += __shfl_xor(s, 32);
;                 const float r = 1.0f / sqrtf(s * (1.0f / 1024.0f) + 1e-6f);
; #pragma unroll
;                 for (int bj = 0; bj < 2; ++bj) { *(f32x4*)(out + off + bj * HALF) = acc[ai][bj][m][0] * r * gv[bj][0]; *(f32x4*)(out + off + bj * HALF + 4) = acc[ai][bj][m][1] * r * gv[bj][1]; }
	v_add_f32_e32 v32, v32, v33
	v_fmamk_f32 v32, v32, 0x3a800000, v217
	v_mul_f32_e32 v33, 0x4f800000, v32
	v_cmp_gt_f32_e32 vcc, s43, v32
	v_pk_mul_f32 v[28:29], v[110:111], v[96:97] op_sel_hi:[1,0]
	v_pk_mul_f32 v[30:31], v[102:103], v[96:97] op_sel_hi:[1,0]
	v_cndmask_b32_e32 v32, v32, v33, vcc
	v_sqrt_f32_e32 v33, v32
	v_pk_mul_f32 v[30:31], v[6:7], v[30:31]
	v_pk_mul_f32 v[28:29], v[4:5], v[28:29]
	global_store_dwordx4 v[106:107], v[28:31], off offset:512
	v_add_u32_e32 v34, -1, v33
	v_fma_f32 v35, -v34, v33, v32
	v_cmp_ge_f32_e64 s[6:7], 0, v35
	v_add_u32_e32 v35, 1, v33
	v_pk_mul_f32 v[28:29], v[104:105], v[96:97] op_sel_hi:[1,0]
	v_cndmask_b32_e64 v34, v33, v34, s[6:7]
	v_fma_f32 v33, -v35, v33, v32
	v_cmp_lt_f32_e64 s[6:7], 0, v33
	v_pk_mul_f32 v[30:31], v[98:99], v[96:97] op_sel_hi:[1,0]
	v_pk_mul_f32 v[28:29], v[0:1], v[28:29]
	v_cndmask_b32_e64 v33, v34, v35, s[6:7]
	v_mul_f32_e32 v34, 0x37800000, v33
	v_cndmask_b32_e32 v33, v33, v34, vcc
	v_cmp_class_f32_e32 vcc, v32, v218
	v_pk_mul_f32 v[30:31], v[2:3], v[30:31]
	global_store_dwordx4 v[106:107], v[28:31], off offset:528
	v_cndmask_b32_e32 v32, v33, v32, vcc
	v_div_scale_f32 v33, s[6:7], v32, v32, 1.0
	v_rcp_f32_e32 v34, v33
	s_nop 0
	v_fma_f32 v28, -v33, v34, 1.0
	v_fmac_f32_e32 v34, v28, v34
	v_div_scale_f32 v28, vcc, 1.0, v32, 1.0
	v_mul_f32_e32 v29, v28, v34
	v_fma_f32 v30, -v33, v29, v28
	v_fmac_f32_e32 v29, v30, v34
	v_fma_f32 v28, -v33, v29, v28
	v_div_fmas_f32 v28, v28, v34, v29
	v_div_fixup_f32 v32, v28, v32, 1.0
	v_lshlrev_b64 v[34:35], 12, v[100:101]
	v_pk_mul_f32 v[28:29], v[198:199], v[32:33] op_sel_hi:[1,0]
	v_pk_mul_f32 v[30:31], v[196:197], v[32:33] op_sel_hi:[1,0]
	v_lshl_add_u64 v[34:35], s[70:71], 0, v[34:35]
	v_pk_mul_f32 v[30:31], v[14:15], v[30:31]
	v_pk_mul_f32 v[28:29], v[12:13], v[28:29]
	v_lshl_add_u64 v[34:35], v[34:35], 0, v[190:191]
	global_store_dwordx4 v[34:35], v[28:31], off
	s_nop 1
	v_mov_b32_e32 v30, v25
	v_mov_b32_e32 v31, v26
	v_mov_b32_e32 v25, v27
	v_pk_add_f32 v[24:25], v[30:31], v[24:25]
	v_pk_mul_f32 v[28:29], v[194:195], v[32:33] op_sel_hi:[1,0]
	v_add_f32_e32 v30, v24, v25
	ds_bpermute_b32 v31, v219, v30
	v_pk_mul_f32 v[24:25], v[58:59], v[32:33] op_sel_hi:[1,0]
	s_nop 0
	v_pk_mul_f32 v[26:27], v[10:11], v[24:25]
	v_pk_mul_f32 v[24:25], v[8:9], v[28:29]
	s_waitcnt lgkmcnt(0)
	v_add_f32_e32 v28, v30, v31
	ds_bpermute_b32 v29, v220, v28
	global_store_dwordx4 v[34:35], v[24:27], off offset:16
	s_waitcnt lgkmcnt(0)
	v_add_f32_e32 v28, v28, v29
	v_fmamk_f32 v28, v28, 0x3a800000, v217
	v_mul_f32_e32 v29, 0x4f800000, v28
	v_cmp_gt_f32_e32 vcc, s43, v28
	v_pk_mul_f32 v[24:25], v[52:53], v[32:33] op_sel_hi:[1,0]
	v_pk_mul_f32 v[26:27], v[54:55], v[32:33] op_sel_hi:[1,0]
	v_cndmask_b32_e32 v28, v28, v29, vcc
	v_sqrt_f32_e32 v29, v28
	v_pk_mul_f32 v[26:27], v[6:7], v[26:27]
	v_pk_mul_f32 v[24:25], v[4:5], v[24:25]
	global_store_dwordx4 v[34:35], v[24:27], off offset:512
	v_add_u32_e32 v30, -1, v29
	v_fma_f32 v31, -v30, v29, v28
	v_cmp_ge_f32_e64 s[6:7], 0, v31
	v_add_u32_e32 v31, 1, v29
	v_pk_mul_f32 v[24:25], v[48:49], v[32:33] op_sel_hi:[1,0]
	v_cndmask_b32_e64 v30, v29, v30, s[6:7]
	v_fma_f32 v29, -v31, v29, v28
	v_cmp_lt_f32_e64 s[6:7], 0, v29
	v_pk_mul_f32 v[26:27], v[50:51], v[32:33] op_sel_hi:[1,0]
	v_pk_mul_f32 v[24:25], v[0:1], v[24:25]
	v_cndmask_b32_e64 v29, v30, v31, s[6:7]
	v_mul_f32_e32 v30, 0x37800000, v29
	v_cndmask_b32_e32 v29, v29, v30, vcc
	v_cmp_class_f32_e32 vcc, v28, v218
	v_pk_mul_f32 v[26:27], v[2:3], v[26:27]
	global_store_dwordx4 v[34:35], v[24:27], off offset:528
	v_cndmask_b32_e32 v28, v29, v28, vcc
	v_div_scale_f32 v29, s[6:7], v28, v28, 1.0
	v_rcp_f32_e32 v30, v29
	s_nop 0
	v_fma_f32 v24, -v29, v30, 1.0
	v_fmac_f32_e32 v30, v24, v30
	v_div_scale_f32 v24, vcc, 1.0, v28, 1.0
	v_mul_f32_e32 v25, v24, v30
	v_fma_f32 v26, -v29, v25, v24
	v_fmac_f32_e32 v25, v26, v30
	v_fma_f32 v24, -v29, v25, v24
	v_div_fmas_f32 v24, v24, v30, v25
	v_div_fixup_f32 v28, v24, v28, 1.0
	v_lshlrev_b64 v[30:31], 12, v[92:93]
	v_pk_mul_f32 v[24:25], v[192:193], v[28:29] op_sel_hi:[1,0]
	v_pk_mul_f32 v[26:27], v[84:85], v[28:29] op_sel_hi:[1,0]
	v_lshl_add_u64 v[30:31], s[70:71], 0, v[30:31]
	v_pk_mul_f32 v[26:27], v[14:15], v[26:27]
	v_pk_mul_f32 v[24:25], v[12:13], v[24:25]
	v_lshl_add_u64 v[30:31], v[30:31], 0, v[190:191]
	global_store_dwordx4 v[30:31], v[24:27], off
	s_waitcnt vmcnt(22)
	s_nop 0
	v_mov_b32_e32 v26, v21
	v_mov_b32_e32 v27, v22
	v_mov_b32_e32 v21, v23
	v_pk_add_f32 v[20:21], v[26:27], v[20:21]
	v_pk_mul_f32 v[24:25], v[86:87], v[28:29] op_sel_hi:[1,0]
	v_add_f32_e32 v26, v20, v21
	ds_bpermute_b32 v27, v219, v26
	v_pk_mul_f32 v[20:21], v[42:43], v[28:29] op_sel_hi:[1,0]
	s_nop 0
	v_pk_mul_f32 v[22:23], v[10:11], v[20:21]
	v_pk_mul_f32 v[20:21], v[8:9], v[24:25]
	s_waitcnt lgkmcnt(0)
	v_add_f32_e32 v24, v26, v27
	ds_bpermute_b32 v25, v220, v24
	global_store_dwordx4 v[30:31], v[20:23], off offset:16
	s_waitcnt lgkmcnt(0)
; #define PG8_BAR __builtin_amdgcn_s_barrier()
;     __device__ __forceinline__ void operator()(f32x4 (&acc)[2][2][4][2], const Unit& u, int wr, int wc, int fr, int fq) const {
;     ...
; #pragma unroll
;         for (int ai = 0; ai < 2; ++ai)
; #pragma unroll
;             for (int m = 0; m < 4; ++m) {
;                 const int row = row0 + ai * HALF + m * 16; const size_t off = (size_t)row * DM + col0;
;                 const f32x4 pt = ptv[ai][m];
;                 float s = (pt[0] + pt[1]) + (pt[2] + pt[3]); s += __shfl_xor(s, 16); s += __shfl_xor(s, 32);
;                 const float r = 1.0f / sqrtf(s * (1.0f / 1024.0f) + 1e-6f);
; #pragma unroll
;                 for (int bj = 0; bj < 2; ++bj) { *(f32x4*)(out + off + bj * HALF) = acc[ai][bj][m][0] * r * gv[bj][0]; *(f32x4*)(out + off + bj * HALF + 4) = acc[ai][bj][m][1] * r * gv[bj][1]; }
; template <class Epi, class Sched, bool ALIGN_EPI = false, bool SP2 = false>
; __device__ __forceinline__ void gemm_phase(PG8_LAS unsigned char* lds, const Gemm g, const Sched& S, const Epi& E) {
;     ...
;         if constexpr (ALIGN_EPI) { if (wr == 0) PG8_BAR; }
;         if constexpr (!Epi::AFTER_DRAIN) { E(acc, cur, wr, wc, fr, fq); S.done(cur); }
;         if (!has_next) break;
; #pragma unroll
;         for (int a = 0; a < 2; ++a)
; #pragma unroll
;             for (int b = 0; b < 2; ++b)
; #pragma unroll
;                 for (int m = 0; m < 4; ++m)
; #pragma unroll
;                     for (int n = 0; n < 2; ++n) acc[a][b][m][n] = (f32x4){0.f, 0.f, 0.f, 0.f};
;         cur = nxt; cA = nA; cB = nB; ++ui;
;         if constexpr (ALIGN_EPI) { if (wr == 1) PG8_BAR; }
	v_add_f32_e32 v24, v24, v25
	v_fmamk_f32 v24, v24, 0x3a800000, v217
	v_mul_f32_e32 v25, 0x4f800000, v24
	v_cmp_gt_f32_e32 vcc, s43, v24
	v_pk_mul_f32 v[20:21], v[80:81], v[28:29] op_sel_hi:[1,0]
	v_pk_mul_f32 v[22:23], v[60:61], v[28:29] op_sel_hi:[1,0]
	v_cndmask_b32_e32 v24, v24, v25, vcc
	v_sqrt_f32_e32 v25, v24
	v_pk_mul_f32 v[22:23], v[6:7], v[22:23]
	v_pk_mul_f32 v[20:21], v[4:5], v[20:21]
	global_store_dwordx4 v[30:31], v[20:23], off offset:512
	v_add_u32_e32 v26, -1, v25
	v_fma_f32 v27, -v26, v25, v24
	v_cmp_ge_f32_e64 s[6:7], 0, v27
	v_add_u32_e32 v27, 1, v25
	v_pk_mul_f32 v[20:21], v[62:63], v[28:29] op_sel_hi:[1,0]
	v_cndmask_b32_e64 v26, v25, v26, s[6:7]
	v_fma_f32 v25, -v27, v25, v24
	v_cmp_lt_f32_e64 s[6:7], 0, v25
	v_pk_mul_f32 v[22:23], v[46:47], v[28:29] op_sel_hi:[1,0]
	v_pk_mul_f32 v[20:21], v[0:1], v[20:21]
	v_cndmask_b32_e64 v25, v26, v27, s[6:7]
	v_mul_f32_e32 v26, 0x37800000, v25
	v_cndmask_b32_e32 v25, v25, v26, vcc
	v_cmp_class_f32_e32 vcc, v24, v218
	v_pk_mul_f32 v[22:23], v[2:3], v[22:23]
	global_store_dwordx4 v[30:31], v[20:23], off offset:528
	v_cndmask_b32_e32 v24, v25, v24, vcc
	v_div_scale_f32 v25, s[6:7], v24, v24, 1.0
	v_rcp_f32_e32 v26, v25
	s_nop 0
	v_fma_f32 v20, -v25, v26, 1.0
	v_fmac_f32_e32 v26, v20, v26
	v_div_scale_f32 v20, vcc, 1.0, v24, 1.0
	v_mul_f32_e32 v21, v20, v26
	v_fma_f32 v22, -v25, v21, v20
	v_fmac_f32_e32 v21, v22, v26
	v_fma_f32 v20, -v25, v21, v20
	v_div_fmas_f32 v20, v20, v26, v21
	v_div_fixup_f32 v24, v20, v24, 1.0
	v_lshlrev_b64 v[26:27], 12, v[90:91]
	v_pk_mul_f32 v[20:21], v[82:83], v[24:25] op_sel_hi:[1,0]
	v_pk_mul_f32 v[22:23], v[76:77], v[24:25] op_sel_hi:[1,0]
	v_lshl_add_u64 v[26:27], s[70:71], 0, v[26:27]
	v_pk_mul_f32 v[22:23], v[14:15], v[22:23]
	v_pk_mul_f32 v[20:21], v[12:13], v[20:21]
	v_lshl_add_u64 v[26:27], v[26:27], 0, v[190:191]
	global_store_dwordx4 v[26:27], v[20:23], off
	s_waitcnt vmcnt(25)
	s_nop 0
	v_mov_b32_e32 v22, v17
	v_mov_b32_e32 v23, v18
	v_mov_b32_e32 v17, v19
	v_pk_add_f32 v[16:17], v[22:23], v[16:17]
	v_pk_mul_f32 v[20:21], v[78:79], v[24:25] op_sel_hi:[1,0]
	v_add_f32_e32 v22, v16, v17
	ds_bpermute_b32 v23, v219, v22
	v_pk_mul_f32 v[16:17], v[36:37], v[24:25] op_sel_hi:[1,0]
	s_nop 0
	v_pk_mul_f32 v[18:19], v[10:11], v[16:17]
	v_pk_mul_f32 v[16:17], v[8:9], v[20:21]
	s_waitcnt lgkmcnt(0)
	v_add_f32_e32 v20, v22, v23
	ds_bpermute_b32 v21, v220, v20
	global_store_dwordx4 v[26:27], v[16:19], off offset:16
	s_waitcnt lgkmcnt(0)
	v_add_f32_e32 v20, v20, v21
	v_fmamk_f32 v20, v20, 0x3a800000, v217
	v_mul_f32_e32 v21, 0x4f800000, v20
	v_cmp_gt_f32_e32 vcc, s43, v20
	v_pk_mul_f32 v[16:17], v[56:57], v[24:25] op_sel_hi:[1,0]
	v_pk_mul_f32 v[18:19], v[40:41], v[24:25] op_sel_hi:[1,0]
	v_cndmask_b32_e32 v20, v20, v21, vcc
	v_sqrt_f32_e32 v21, v20
	v_pk_mul_f32 v[18:19], v[6:7], v[18:19]
	v_pk_mul_f32 v[16:17], v[4:5], v[16:17]
	global_store_dwordx4 v[26:27], v[16:19], off offset:512
	v_add_u32_e32 v22, -1, v21
	v_fma_f32 v23, -v22, v21, v20
	v_cmp_ge_f32_e64 s[6:7], 0, v23
	v_add_u32_e32 v23, 1, v21
	v_pk_mul_f32 v[16:17], v[44:45], v[24:25] op_sel_hi:[1,0]
	v_cndmask_b32_e64 v22, v21, v22, s[6:7]
	v_fma_f32 v21, -v23, v21, v20
	v_cmp_lt_f32_e64 s[6:7], 0, v21
	v_pk_mul_f32 v[18:19], v[38:39], v[24:25] op_sel_hi:[1,0]
	v_pk_mul_f32 v[16:17], v[0:1], v[16:17]
	v_cndmask_b32_e64 v21, v22, v23, s[6:7]
	v_mul_f32_e32 v22, 0x37800000, v21
	v_cndmask_b32_e32 v21, v21, v22, vcc
	v_cmp_class_f32_e32 vcc, v20, v218
	v_pk_mul_f32 v[18:19], v[2:3], v[18:19]
	global_store_dwordx4 v[26:27], v[16:19], off offset:528
	v_cndmask_b32_e32 v20, v21, v20, vcc
	v_div_scale_f32 v21, s[6:7], v20, v20, 1.0
	v_rcp_f32_e32 v22, v21
	s_nop 0
	v_fma_f32 v16, -v21, v22, 1.0
	v_fmac_f32_e32 v22, v16, v22
	v_div_scale_f32 v16, vcc, 1.0, v20, 1.0
	v_mul_f32_e32 v17, v16, v22
	v_fma_f32 v18, -v21, v17, v16
	v_fmac_f32_e32 v17, v18, v22
	v_fma_f32 v16, -v21, v17, v16
	v_div_fmas_f32 v16, v16, v22, v17
	v_div_fixup_f32 v16, v16, v20, 1.0
	v_pk_mul_f32 v[18:19], v[74:75], v[16:17] op_sel_hi:[1,0]
	v_pk_mul_f32 v[20:21], v[70:71], v[16:17] op_sel_hi:[1,0]
	v_pk_mul_f32 v[12:13], v[12:13], v[18:19]
	v_lshlrev_b64 v[18:19], 12, v[88:89]
	v_lshl_add_u64 v[18:19], s[70:71], 0, v[18:19]
	v_pk_mul_f32 v[14:15], v[14:15], v[20:21]
	v_lshl_add_u64 v[18:19], v[18:19], 0, v[190:191]
	global_store_dwordx4 v[18:19], v[12:15], off
	s_and_b64 vcc, exec, s[4:5]
	s_mov_b64 s[4:5], -1
	v_pk_mul_f32 v[12:13], v[72:73], v[16:17] op_sel_hi:[1,0]
	v_pk_mul_f32 v[14:15], v[68:69], v[16:17] op_sel_hi:[1,0]
	v_pk_mul_f32 v[8:9], v[8:9], v[12:13]
	v_pk_mul_f32 v[10:11], v[10:11], v[14:15]
	global_store_dwordx4 v[18:19], v[8:11], off offset:16
	s_nop 1
	v_pk_mul_f32 v[8:9], v[130:131], v[16:17] op_sel_hi:[1,0]
	v_pk_mul_f32 v[10:11], v[66:67], v[16:17] op_sel_hi:[1,0]
	v_pk_mul_f32 v[4:5], v[4:5], v[8:9]
	v_pk_mul_f32 v[6:7], v[6:7], v[10:11]
	global_store_dwordx4 v[18:19], v[4:7], off offset:512
	s_nop 1
	v_pk_mul_f32 v[4:5], v[128:129], v[16:17] op_sel_hi:[1,0]
	v_pk_mul_f32 v[6:7], v[64:65], v[16:17] op_sel_hi:[1,0]
	v_pk_mul_f32 v[0:1], v[0:1], v[4:5]
	v_pk_mul_f32 v[2:3], v[2:3], v[6:7]
	global_store_dwordx4 v[18:19], v[0:3], off offset:528
	s_cbranch_vccnz .LBB0_1430
	s_andn2_b64 vcc, exec, s[14:15]
	s_cbranch_vccnz .LBB0_1429
	s_barrier
	s_branch .LBB0_1429
